# main GEMM compute phases: the second s_waitcnt lgkmcnt(0) after the barrier (nothing outstanding) removed from the MFMA wave's path
# speedup vs baseline: 1.0016x; 1.0016x over previous
.Lkl_first:
	s_add_i32 s87, s86, 2
	s_add_u32 s30, s8, 0x80
	s_addc_u32 s31, s9, 0
	s_add_i32 s88, 16, 0x10000
	s_cmp_eq_u32 s57, s60
	s_cselect_b32 s31, s25, s31
	s_cselect_b32 s30, s24, s30
	v_add_u32_e32 v0, s88, v237
	s_cselect_b32 vcc_hi, s27, s85
	s_cselect_b32 vcc_lo, s26, s84
	s_add_i32 s89, 16, 0x14000
	ds_read_b128 v[132:135], v0
	ds_read_b128 v[136:139], v0 offset:1024
	ds_read_b128 v[152:155], v0 offset:2048
	ds_read_b128 v[156:159], v0 offset:3072
	v_add_u32_e32 v0, s89, v237
	ds_read_b128 v[160:163], v0
	ds_read_b128 v[164:167], v0 offset:1024
	ds_read_b128 v[168:171], v0 offset:2048
	ds_read_b128 v[172:175], v0 offset:3072
	v_lshl_add_u64 v[2:3], s[8:9], 0, v[150:151]
	s_add_i32 m0, s95, 0xc000
	ds_read_b128 v[176:179], v246
	ds_read_b128 v[180:183], v246 offset:1024
	ds_read_b128 v[184:187], v246 offset:2048
	ds_read_b128 v[188:191], v246 offset:3072
	ds_read_b128 v[192:195], v246 offset:4096
	ds_read_b128 v[196:199], v246 offset:5120
	ds_read_b128 v[200:203], v246 offset:6144
	ds_read_b128 v[204:207], v246 offset:7168
	global_load_lds_dwordx4 v[2:3], off
	v_lshl_add_u64 v[2:3], s[8:9], 0, v[148:149]
	s_add_i32 m0, s95, 0xe000
	s_nop 0
	global_load_lds_dwordx4 v[2:3], off
	s_waitcnt vmcnt(8)
	s_waitcnt lgkmcnt(0)
	s_barrier
	s_setprio 1
	v_mfma_f32_16x16x32_bf16 v[128:131], v[132:135], v[176:179], 0
	v_mfma_f32_16x16x32_bf16 v[124:127], v[152:155], v[176:179], 0
	v_mfma_f32_16x16x32_bf16 v[112:115], v[132:135], v[184:187], 0
	v_mfma_f32_16x16x32_bf16 v[108:111], v[152:155], v[184:187], 0
	v_mfma_f32_16x16x32_bf16 v[96:99], v[132:135], v[192:195], 0
	v_mfma_f32_16x16x32_bf16 v[92:95], v[152:155], v[192:195], 0
	v_mfma_f32_16x16x32_bf16 v[80:83], v[132:135], v[200:203], 0
	v_mfma_f32_16x16x32_bf16 v[76:79], v[152:155], v[200:203], 0
	v_mfma_f32_16x16x32_bf16 v[128:131], v[136:139], v[180:183], v[128:131]
	v_mfma_f32_16x16x32_bf16 v[124:127], v[156:159], v[180:183], v[124:127]
	v_mfma_f32_16x16x32_bf16 v[112:115], v[136:139], v[188:191], v[112:115]
	v_mfma_f32_16x16x32_bf16 v[108:111], v[156:159], v[188:191], v[108:111]
	v_mfma_f32_16x16x32_bf16 v[96:99], v[136:139], v[196:199], v[96:99]
	v_mfma_f32_16x16x32_bf16 v[92:95], v[156:159], v[196:199], v[92:95]
	v_mfma_f32_16x16x32_bf16 v[80:83], v[136:139], v[204:207], v[80:83]
	v_mfma_f32_16x16x32_bf16 v[76:79], v[156:159], v[204:207], v[76:79]
	s_setprio 0
	s_setprio 1
	v_mfma_f32_16x16x32_bf16 v[120:123], v[160:163], v[176:179], 0
	v_mfma_f32_16x16x32_bf16 v[116:119], v[168:171], v[176:179], 0
	v_mfma_f32_16x16x32_bf16 v[104:107], v[160:163], v[184:187], 0
	v_mfma_f32_16x16x32_bf16 v[100:103], v[168:171], v[184:187], 0
	v_mfma_f32_16x16x32_bf16 v[88:91], v[160:163], v[192:195], 0
	v_mfma_f32_16x16x32_bf16 v[84:87], v[168:171], v[192:195], 0
	v_mfma_f32_16x16x32_bf16 v[72:75], v[160:163], v[200:203], 0
	v_mfma_f32_16x16x32_bf16 v[68:71], v[168:171], v[200:203], 0
	v_mfma_f32_16x16x32_bf16 v[120:123], v[164:167], v[180:183], v[120:123]
	v_mfma_f32_16x16x32_bf16 v[116:119], v[172:175], v[180:183], v[116:119]
	v_mfma_f32_16x16x32_bf16 v[104:107], v[164:167], v[188:191], v[104:107]
	v_mfma_f32_16x16x32_bf16 v[100:103], v[172:175], v[188:191], v[100:103]
	v_mfma_f32_16x16x32_bf16 v[88:91], v[164:167], v[196:199], v[88:91]
	v_mfma_f32_16x16x32_bf16 v[84:87], v[172:175], v[196:199], v[84:87]
	v_mfma_f32_16x16x32_bf16 v[72:75], v[164:167], v[204:207], v[72:75]
	v_mfma_f32_16x16x32_bf16 v[68:71], v[172:175], v[204:207], v[68:71]
	s_setprio 0
	s_barrier
	s_add_i32 s88, s88, s93
	v_lshl_add_u64 v[208:209], vcc, 0, v[142:143]
	s_mov_b32 m0, s88
	ds_read_b128 v[176:179], v246 offset:16384
	ds_read_b128 v[180:183], v246 offset:17408
	ds_read_b128 v[184:187], v246 offset:18432
	ds_read_b128 v[188:191], v246 offset:19456
	ds_read_b128 v[192:195], v246 offset:20480
	ds_read_b128 v[196:199], v246 offset:21504
	ds_read_b128 v[200:203], v246 offset:22528
	ds_read_b128 v[204:207], v246 offset:23552
	global_load_lds_dwordx4 v[208:209], off
	s_add_i32 m0, s88, 0x2000
	v_lshl_add_u64 v[210:211], vcc, 0, v[144:145]
	s_add_u32 vcc_lo, vcc_lo, s18
	s_addc_u32 vcc_hi, vcc_hi, 0
	s_add_i32 s88, s89, s93
	global_load_lds_dwordx4 v[210:211], off
	v_lshl_add_u64 v[212:213], vcc, 0, v[142:143]
	s_mov_b32 m0, s88
	v_lshl_add_u64 v[214:215], vcc, 0, v[144:145]
	global_load_lds_dwordx4 v[212:213], off
	s_add_i32 m0, s88, 0x2000
	v_lshl_add_u64 v[224:225], s[30:31], 0, v[142:143]
	global_load_lds_dwordx4 v[214:215], off
	s_mov_b32 m0, s95
	v_lshl_add_u64 v[226:227], s[30:31], 0, v[144:145]
	global_load_lds_dwordx4 v[224:225], off
	s_mov_b32 m0, s96
	s_nop 0
	global_load_lds_dwordx4 v[226:227], off
	s_waitcnt vmcnt(8)
	s_waitcnt lgkmcnt(0)
	s_barrier
	s_setprio 1
	v_mfma_f32_16x16x32_bf16 v[64:67], v[132:135], v[176:179], 0
	v_mfma_f32_16x16x32_bf16 v[60:63], v[152:155], v[176:179], 0
	v_mfma_f32_16x16x32_bf16 v[48:51], v[132:135], v[184:187], 0
	v_mfma_f32_16x16x32_bf16 v[44:47], v[152:155], v[184:187], 0
	v_mfma_f32_16x16x32_bf16 v[32:35], v[132:135], v[192:195], 0
	v_mfma_f32_16x16x32_bf16 v[28:31], v[152:155], v[192:195], 0
	v_mfma_f32_16x16x32_bf16 v[16:19], v[132:135], v[200:203], 0
	v_mfma_f32_16x16x32_bf16 v[12:15], v[152:155], v[200:203], 0
	v_mfma_f32_16x16x32_bf16 v[64:67], v[136:139], v[180:183], v[64:67]
	v_mfma_f32_16x16x32_bf16 v[60:63], v[156:159], v[180:183], v[60:63]
	v_mfma_f32_16x16x32_bf16 v[48:51], v[136:139], v[188:191], v[48:51]
	v_mfma_f32_16x16x32_bf16 v[44:47], v[156:159], v[188:191], v[44:47]
	v_mfma_f32_16x16x32_bf16 v[32:35], v[136:139], v[196:199], v[32:35]
	v_mfma_f32_16x16x32_bf16 v[28:31], v[156:159], v[196:199], v[28:31]
	v_mfma_f32_16x16x32_bf16 v[16:19], v[136:139], v[204:207], v[16:19]
	v_mfma_f32_16x16x32_bf16 v[12:15], v[156:159], v[204:207], v[12:15]
	s_setprio 0
	s_setprio 1
	v_mfma_f32_16x16x32_bf16 v[56:59], v[160:163], v[176:179], 0
	v_mfma_f32_16x16x32_bf16 v[52:55], v[168:171], v[176:179], 0
	v_mfma_f32_16x16x32_bf16 v[40:43], v[160:163], v[184:187], 0
	v_mfma_f32_16x16x32_bf16 v[36:39], v[168:171], v[184:187], 0
	v_mfma_f32_16x16x32_bf16 v[24:27], v[160:163], v[192:195], 0
	v_mfma_f32_16x16x32_bf16 v[20:23], v[168:171], v[192:195], 0
	v_mfma_f32_16x16x32_bf16 v[8:11], v[160:163], v[200:203], 0
	v_mfma_f32_16x16x32_bf16 v[2:5], v[168:171], v[200:203], 0
	v_mfma_f32_16x16x32_bf16 v[56:59], v[164:167], v[180:183], v[56:59]
	v_mfma_f32_16x16x32_bf16 v[52:55], v[172:175], v[180:183], v[52:55]
	v_mfma_f32_16x16x32_bf16 v[40:43], v[164:167], v[188:191], v[40:43]
	v_mfma_f32_16x16x32_bf16 v[36:39], v[172:175], v[188:191], v[36:39]
	v_mfma_f32_16x16x32_bf16 v[24:27], v[164:167], v[196:199], v[24:27]
	v_mfma_f32_16x16x32_bf16 v[20:23], v[172:175], v[196:199], v[20:23]
	v_mfma_f32_16x16x32_bf16 v[8:11], v[164:167], v[204:207], v[8:11]
	v_mfma_f32_16x16x32_bf16 v[2:5], v[172:175], v[204:207], v[2:5]
	s_setprio 0
	s_barrier
	s_add_i32 s88, 16, 0x18000
	v_add_u32_e32 v0, s88, v237
	s_add_i32 s89, 16, 0x1c000
	ds_read_b128 v[132:135], v0
	ds_read_b128 v[136:139], v0 offset:1024
	ds_read_b128 v[152:155], v0 offset:2048
	ds_read_b128 v[156:159], v0 offset:3072
	v_add_u32_e32 v0, s89, v237
	ds_read_b128 v[160:163], v0
	ds_read_b128 v[164:167], v0 offset:1024
	ds_read_b128 v[168:171], v0 offset:2048
	ds_read_b128 v[172:175], v0 offset:3072
	s_add_u32 s30, s30, s18
	s_addc_u32 s31, s31, 0
	s_mov_b32 m0, s97
	v_lshl_add_u64 v[6:7], s[30:31], 0, v[142:143]
	ds_read_b128 v[176:179], v246 offset:32768
	ds_read_b128 v[180:183], v246 offset:33792
	ds_read_b128 v[184:187], v246 offset:34816
	ds_read_b128 v[188:191], v246 offset:35840
	ds_read_b128 v[192:195], v246 offset:36864
	ds_read_b128 v[196:199], v246 offset:37888
	ds_read_b128 v[200:203], v246 offset:38912
	ds_read_b128 v[204:207], v246 offset:39936
	global_load_lds_dwordx4 v[6:7], off
	v_lshl_add_u64 v[6:7], s[30:31], 0, v[144:145]
	s_mov_b32 m0, s58
	s_nop 0
	global_load_lds_dwordx4 v[6:7], off
	s_waitcnt vmcnt(8)
	s_waitcnt lgkmcnt(0)
	s_barrier
	s_setprio 1
	v_mfma_f32_16x16x32_bf16 v[128:131], v[132:135], v[176:179], v[128:131]
	v_mfma_f32_16x16x32_bf16 v[124:127], v[152:155], v[176:179], v[124:127]
	v_mfma_f32_16x16x32_bf16 v[112:115], v[132:135], v[184:187], v[112:115]
	v_mfma_f32_16x16x32_bf16 v[108:111], v[152:155], v[184:187], v[108:111]
	v_mfma_f32_16x16x32_bf16 v[96:99], v[132:135], v[192:195], v[96:99]
	v_mfma_f32_16x16x32_bf16 v[92:95], v[152:155], v[192:195], v[92:95]
	v_mfma_f32_16x16x32_bf16 v[80:83], v[132:135], v[200:203], v[80:83]
	v_mfma_f32_16x16x32_bf16 v[76:79], v[152:155], v[200:203], v[76:79]
	v_mfma_f32_16x16x32_bf16 v[128:131], v[136:139], v[180:183], v[128:131]
	v_mfma_f32_16x16x32_bf16 v[124:127], v[156:159], v[180:183], v[124:127]
	v_mfma_f32_16x16x32_bf16 v[112:115], v[136:139], v[188:191], v[112:115]
	v_mfma_f32_16x16x32_bf16 v[108:111], v[156:159], v[188:191], v[108:111]
	v_mfma_f32_16x16x32_bf16 v[96:99], v[136:139], v[196:199], v[96:99]
	v_mfma_f32_16x16x32_bf16 v[92:95], v[156:159], v[196:199], v[92:95]
	v_mfma_f32_16x16x32_bf16 v[80:83], v[136:139], v[204:207], v[80:83]
	v_mfma_f32_16x16x32_bf16 v[76:79], v[156:159], v[204:207], v[76:79]
	s_setprio 0
	s_setprio 1
	v_mfma_f32_16x16x32_bf16 v[120:123], v[160:163], v[176:179], v[120:123]
	v_mfma_f32_16x16x32_bf16 v[116:119], v[168:171], v[176:179], v[116:119]
	v_mfma_f32_16x16x32_bf16 v[104:107], v[160:163], v[184:187], v[104:107]
	v_mfma_f32_16x16x32_bf16 v[100:103], v[168:171], v[184:187], v[100:103]
	v_mfma_f32_16x16x32_bf16 v[88:91], v[160:163], v[192:195], v[88:91]
	v_mfma_f32_16x16x32_bf16 v[84:87], v[168:171], v[192:195], v[84:87]
	v_mfma_f32_16x16x32_bf16 v[72:75], v[160:163], v[200:203], v[72:75]
	v_mfma_f32_16x16x32_bf16 v[68:71], v[168:171], v[200:203], v[68:71]
	v_mfma_f32_16x16x32_bf16 v[120:123], v[164:167], v[180:183], v[120:123]
	v_mfma_f32_16x16x32_bf16 v[116:119], v[172:175], v[180:183], v[116:119]
	v_mfma_f32_16x16x32_bf16 v[104:107], v[164:167], v[188:191], v[104:107]
	v_mfma_f32_16x16x32_bf16 v[100:103], v[172:175], v[188:191], v[100:103]
	v_mfma_f32_16x16x32_bf16 v[88:91], v[164:167], v[196:199], v[88:91]
	v_mfma_f32_16x16x32_bf16 v[84:87], v[172:175], v[196:199], v[84:87]
	v_mfma_f32_16x16x32_bf16 v[72:75], v[164:167], v[204:207], v[72:75]
	v_mfma_f32_16x16x32_bf16 v[68:71], v[172:175], v[204:207], v[68:71]
	s_setprio 0
	s_barrier
	s_add_i32 s30, s88, s93
	v_lshl_add_u64 v[6:7], v[208:209], 0, s[36:37]
	s_mov_b32 m0, s30
	ds_read_b128 v[176:179], v246 offset:49152
	ds_read_b128 v[180:183], v246 offset:50176
	ds_read_b128 v[184:187], v246 offset:51200
	ds_read_b128 v[188:191], v246 offset:52224
	ds_read_b128 v[192:195], v246 offset:53248
	ds_read_b128 v[196:199], v246 offset:54272
	ds_read_b128 v[200:203], v246 offset:55296
	ds_read_b128 v[204:207], v246 offset:56320
	global_load_lds_dwordx4 v[6:7], off
	v_lshl_add_u64 v[6:7], v[210:211], 0, s[36:37]
	s_add_i32 m0, s30, 0x2000
	s_add_i32 s30, s89, s93
	global_load_lds_dwordx4 v[6:7], off
	v_lshl_add_u64 v[6:7], v[212:213], 0, s[36:37]
	s_mov_b32 m0, s30
	s_nop 0
	global_load_lds_dwordx4 v[6:7], off
	v_lshl_add_u64 v[6:7], v[214:215], 0, s[36:37]
	s_add_i32 m0, s30, 0x2000
	s_nop 0
	global_load_lds_dwordx4 v[6:7], off
	v_lshl_add_u64 v[6:7], v[224:225], 0, s[36:37]
	s_mov_b32 m0, s21
	s_nop 0
	global_load_lds_dwordx4 v[6:7], off
	v_lshl_add_u64 v[6:7], v[226:227], 0, s[36:37]
	s_mov_b32 m0, s33
	s_nop 0
	global_load_lds_dwordx4 v[6:7], off
	s_waitcnt vmcnt(8)
	s_waitcnt lgkmcnt(0)
	s_barrier
	s_setprio 1
	v_mfma_f32_16x16x32_bf16 v[64:67], v[132:135], v[176:179], v[64:67]
	v_mfma_f32_16x16x32_bf16 v[60:63], v[152:155], v[176:179], v[60:63]
	v_mfma_f32_16x16x32_bf16 v[48:51], v[132:135], v[184:187], v[48:51]
	v_mfma_f32_16x16x32_bf16 v[44:47], v[152:155], v[184:187], v[44:47]
	v_mfma_f32_16x16x32_bf16 v[32:35], v[132:135], v[192:195], v[32:35]
	v_mfma_f32_16x16x32_bf16 v[28:31], v[152:155], v[192:195], v[28:31]
	v_mfma_f32_16x16x32_bf16 v[16:19], v[132:135], v[200:203], v[16:19]
	v_mfma_f32_16x16x32_bf16 v[12:15], v[152:155], v[200:203], v[12:15]
	v_mfma_f32_16x16x32_bf16 v[64:67], v[136:139], v[180:183], v[64:67]
	v_mfma_f32_16x16x32_bf16 v[60:63], v[156:159], v[180:183], v[60:63]
	v_mfma_f32_16x16x32_bf16 v[48:51], v[136:139], v[188:191], v[48:51]
	v_mfma_f32_16x16x32_bf16 v[44:47], v[156:159], v[188:191], v[44:47]
	v_mfma_f32_16x16x32_bf16 v[32:35], v[136:139], v[196:199], v[32:35]
	v_mfma_f32_16x16x32_bf16 v[28:31], v[156:159], v[196:199], v[28:31]
	v_mfma_f32_16x16x32_bf16 v[16:19], v[136:139], v[204:207], v[16:19]
	v_mfma_f32_16x16x32_bf16 v[12:15], v[156:159], v[204:207], v[12:15]
	s_setprio 0
	s_setprio 1
	v_mfma_f32_16x16x32_bf16 v[56:59], v[160:163], v[176:179], v[56:59]
	v_mfma_f32_16x16x32_bf16 v[52:55], v[168:171], v[176:179], v[52:55]
	v_mfma_f32_16x16x32_bf16 v[40:43], v[160:163], v[184:187], v[40:43]
	v_mfma_f32_16x16x32_bf16 v[36:39], v[168:171], v[184:187], v[36:39]
	v_mfma_f32_16x16x32_bf16 v[24:27], v[160:163], v[192:195], v[24:27]
	v_mfma_f32_16x16x32_bf16 v[20:23], v[168:171], v[192:195], v[20:23]
	v_mfma_f32_16x16x32_bf16 v[6:9], v[160:163], v[200:203], v[8:11]
	v_mfma_f32_16x16x32_bf16 v[2:5], v[168:171], v[200:203], v[2:5]
	v_mfma_f32_16x16x32_bf16 v[56:59], v[164:167], v[180:183], v[56:59]
	v_mfma_f32_16x16x32_bf16 v[52:55], v[172:175], v[180:183], v[52:55]
	v_mfma_f32_16x16x32_bf16 v[40:43], v[164:167], v[188:191], v[40:43]
	v_mfma_f32_16x16x32_bf16 v[36:39], v[172:175], v[188:191], v[36:39]
	v_mfma_f32_16x16x32_bf16 v[24:27], v[164:167], v[196:199], v[24:27]
	v_mfma_f32_16x16x32_bf16 v[20:23], v[172:175], v[196:199], v[20:23]
	v_mfma_f32_16x16x32_bf16 v[8:11], v[164:167], v[204:207], v[6:9]
	v_mfma_f32_16x16x32_bf16 v[4:7], v[172:175], v[204:207], v[2:5]
	s_setprio 0
	s_barrier
	s_andn2_b64 vcc, exec, s[22:23]
	s_cbranch_vccnz .LBB0_1202
	s_branch .Lkl_1200
.LBB0_1199:
	s_add_i32 s87, s86, 2
	s_add_u32 s30, s8, 0x80
	s_addc_u32 s31, s9, 0
	s_add_i32 s88, 16, 0x10000
	s_cmp_eq_u32 s57, s60
	s_cselect_b32 s31, s25, s31
	s_cselect_b32 s30, s24, s30
	v_add_u32_e32 v0, s88, v237
	s_cselect_b32 vcc_hi, s27, s85
	s_cselect_b32 vcc_lo, s26, s84
	s_add_i32 s89, 16, 0x14000
	ds_read_b128 v[132:135], v0
	ds_read_b128 v[136:139], v0 offset:1024
	ds_read_b128 v[152:155], v0 offset:2048
	ds_read_b128 v[156:159], v0 offset:3072
	v_add_u32_e32 v0, s89, v237
	ds_read_b128 v[160:163], v0
	ds_read_b128 v[164:167], v0 offset:1024
	ds_read_b128 v[168:171], v0 offset:2048
	ds_read_b128 v[172:175], v0 offset:3072
	v_lshl_add_u64 v[2:3], s[8:9], 0, v[150:151]
	s_add_i32 m0, s95, 0xc000
	ds_read_b128 v[176:179], v246
	ds_read_b128 v[180:183], v246 offset:1024
	ds_read_b128 v[184:187], v246 offset:2048
	ds_read_b128 v[188:191], v246 offset:3072
	ds_read_b128 v[192:195], v246 offset:4096
	ds_read_b128 v[196:199], v246 offset:5120
	ds_read_b128 v[200:203], v246 offset:6144
	ds_read_b128 v[204:207], v246 offset:7168
	global_load_lds_dwordx4 v[2:3], off
	v_lshl_add_u64 v[2:3], s[8:9], 0, v[148:149]
	s_add_i32 m0, s95, 0xe000
	s_nop 0
	global_load_lds_dwordx4 v[2:3], off
	s_waitcnt vmcnt(8)
	s_waitcnt lgkmcnt(0)
	s_barrier
	s_setprio 1
	v_mfma_f32_16x16x32_bf16 v[128:131], v[132:135], v[176:179], v[128:131]
	v_mfma_f32_16x16x32_bf16 v[124:127], v[152:155], v[176:179], v[124:127]
	v_mfma_f32_16x16x32_bf16 v[112:115], v[132:135], v[184:187], v[112:115]
	v_mfma_f32_16x16x32_bf16 v[108:111], v[152:155], v[184:187], v[108:111]
	v_mfma_f32_16x16x32_bf16 v[96:99], v[132:135], v[192:195], v[96:99]
	v_mfma_f32_16x16x32_bf16 v[92:95], v[152:155], v[192:195], v[92:95]
	v_mfma_f32_16x16x32_bf16 v[80:83], v[132:135], v[200:203], v[80:83]
	v_mfma_f32_16x16x32_bf16 v[76:79], v[152:155], v[200:203], v[76:79]
	v_mfma_f32_16x16x32_bf16 v[128:131], v[136:139], v[180:183], v[128:131]
	v_mfma_f32_16x16x32_bf16 v[124:127], v[156:159], v[180:183], v[124:127]
	v_mfma_f32_16x16x32_bf16 v[112:115], v[136:139], v[188:191], v[112:115]
	v_mfma_f32_16x16x32_bf16 v[108:111], v[156:159], v[188:191], v[108:111]
	v_mfma_f32_16x16x32_bf16 v[96:99], v[136:139], v[196:199], v[96:99]
	v_mfma_f32_16x16x32_bf16 v[92:95], v[156:159], v[196:199], v[92:95]
	v_mfma_f32_16x16x32_bf16 v[80:83], v[136:139], v[204:207], v[80:83]
	v_mfma_f32_16x16x32_bf16 v[76:79], v[156:159], v[204:207], v[76:79]
	s_setprio 0
	s_setprio 1
	v_mfma_f32_16x16x32_bf16 v[120:123], v[160:163], v[176:179], v[120:123]
	v_mfma_f32_16x16x32_bf16 v[116:119], v[168:171], v[176:179], v[116:119]
	v_mfma_f32_16x16x32_bf16 v[104:107], v[160:163], v[184:187], v[104:107]
	v_mfma_f32_16x16x32_bf16 v[100:103], v[168:171], v[184:187], v[100:103]
	v_mfma_f32_16x16x32_bf16 v[88:91], v[160:163], v[192:195], v[88:91]
	v_mfma_f32_16x16x32_bf16 v[84:87], v[168:171], v[192:195], v[84:87]
	v_mfma_f32_16x16x32_bf16 v[72:75], v[160:163], v[200:203], v[72:75]
	v_mfma_f32_16x16x32_bf16 v[68:71], v[168:171], v[200:203], v[68:71]
	v_mfma_f32_16x16x32_bf16 v[120:123], v[164:167], v[180:183], v[120:123]
	v_mfma_f32_16x16x32_bf16 v[116:119], v[172:175], v[180:183], v[116:119]
	v_mfma_f32_16x16x32_bf16 v[104:107], v[164:167], v[188:191], v[104:107]
	v_mfma_f32_16x16x32_bf16 v[100:103], v[172:175], v[188:191], v[100:103]
	v_mfma_f32_16x16x32_bf16 v[88:91], v[164:167], v[196:199], v[88:91]
	v_mfma_f32_16x16x32_bf16 v[84:87], v[172:175], v[196:199], v[84:87]
	v_mfma_f32_16x16x32_bf16 v[72:75], v[164:167], v[204:207], v[72:75]
	v_mfma_f32_16x16x32_bf16 v[68:71], v[172:175], v[204:207], v[68:71]
	s_setprio 0
	s_barrier
	s_add_i32 s88, s88, s93
	v_lshl_add_u64 v[208:209], vcc, 0, v[142:143]
	s_mov_b32 m0, s88
	ds_read_b128 v[176:179], v246 offset:16384
	ds_read_b128 v[180:183], v246 offset:17408
	ds_read_b128 v[184:187], v246 offset:18432
	ds_read_b128 v[188:191], v246 offset:19456
	ds_read_b128 v[192:195], v246 offset:20480
	ds_read_b128 v[196:199], v246 offset:21504
	ds_read_b128 v[200:203], v246 offset:22528
	ds_read_b128 v[204:207], v246 offset:23552
	global_load_lds_dwordx4 v[208:209], off
	s_add_i32 m0, s88, 0x2000
	v_lshl_add_u64 v[210:211], vcc, 0, v[144:145]
	s_add_u32 vcc_lo, vcc_lo, s18
	s_addc_u32 vcc_hi, vcc_hi, 0
	s_add_i32 s88, s89, s93
	global_load_lds_dwordx4 v[210:211], off
	v_lshl_add_u64 v[212:213], vcc, 0, v[142:143]
	s_mov_b32 m0, s88
	v_lshl_add_u64 v[214:215], vcc, 0, v[144:145]
	global_load_lds_dwordx4 v[212:213], off
	s_add_i32 m0, s88, 0x2000
	v_lshl_add_u64 v[224:225], s[30:31], 0, v[142:143]
	global_load_lds_dwordx4 v[214:215], off
	s_mov_b32 m0, s95
	v_lshl_add_u64 v[226:227], s[30:31], 0, v[144:145]
	global_load_lds_dwordx4 v[224:225], off
	s_mov_b32 m0, s96
	s_nop 0
	global_load_lds_dwordx4 v[226:227], off
	s_waitcnt vmcnt(8)
	s_waitcnt lgkmcnt(0)
	s_barrier
	s_setprio 1
	v_mfma_f32_16x16x32_bf16 v[64:67], v[132:135], v[176:179], v[64:67]
	v_mfma_f32_16x16x32_bf16 v[60:63], v[152:155], v[176:179], v[60:63]
	v_mfma_f32_16x16x32_bf16 v[48:51], v[132:135], v[184:187], v[48:51]
	v_mfma_f32_16x16x32_bf16 v[44:47], v[152:155], v[184:187], v[44:47]
	v_mfma_f32_16x16x32_bf16 v[32:35], v[132:135], v[192:195], v[32:35]
	v_mfma_f32_16x16x32_bf16 v[28:31], v[152:155], v[192:195], v[28:31]
	v_mfma_f32_16x16x32_bf16 v[16:19], v[132:135], v[200:203], v[16:19]
	v_mfma_f32_16x16x32_bf16 v[12:15], v[152:155], v[200:203], v[12:15]
	v_mfma_f32_16x16x32_bf16 v[64:67], v[136:139], v[180:183], v[64:67]
	v_mfma_f32_16x16x32_bf16 v[60:63], v[156:159], v[180:183], v[60:63]
	v_mfma_f32_16x16x32_bf16 v[48:51], v[136:139], v[188:191], v[48:51]
	v_mfma_f32_16x16x32_bf16 v[44:47], v[156:159], v[188:191], v[44:47]
	v_mfma_f32_16x16x32_bf16 v[32:35], v[136:139], v[196:199], v[32:35]
	v_mfma_f32_16x16x32_bf16 v[28:31], v[156:159], v[196:199], v[28:31]
	v_mfma_f32_16x16x32_bf16 v[16:19], v[136:139], v[204:207], v[16:19]
	v_mfma_f32_16x16x32_bf16 v[12:15], v[156:159], v[204:207], v[12:15]
	s_setprio 0
	s_setprio 1
	v_mfma_f32_16x16x32_bf16 v[56:59], v[160:163], v[176:179], v[56:59]
	v_mfma_f32_16x16x32_bf16 v[52:55], v[168:171], v[176:179], v[52:55]
	v_mfma_f32_16x16x32_bf16 v[40:43], v[160:163], v[184:187], v[40:43]
	v_mfma_f32_16x16x32_bf16 v[36:39], v[168:171], v[184:187], v[36:39]
	v_mfma_f32_16x16x32_bf16 v[24:27], v[160:163], v[192:195], v[24:27]
	v_mfma_f32_16x16x32_bf16 v[20:23], v[168:171], v[192:195], v[20:23]
	v_mfma_f32_16x16x32_bf16 v[8:11], v[160:163], v[200:203], v[8:11]
	v_mfma_f32_16x16x32_bf16 v[2:5], v[168:171], v[200:203], v[4:7]
	v_mfma_f32_16x16x32_bf16 v[56:59], v[164:167], v[180:183], v[56:59]
	v_mfma_f32_16x16x32_bf16 v[52:55], v[172:175], v[180:183], v[52:55]
	v_mfma_f32_16x16x32_bf16 v[40:43], v[164:167], v[188:191], v[40:43]
	v_mfma_f32_16x16x32_bf16 v[36:39], v[172:175], v[188:191], v[36:39]
	v_mfma_f32_16x16x32_bf16 v[24:27], v[164:167], v[196:199], v[24:27]
	v_mfma_f32_16x16x32_bf16 v[20:23], v[172:175], v[196:199], v[20:23]
	v_mfma_f32_16x16x32_bf16 v[8:11], v[164:167], v[204:207], v[8:11]
	v_mfma_f32_16x16x32_bf16 v[2:5], v[172:175], v[204:207], v[2:5]
	s_setprio 0
	s_barrier
	s_add_i32 s88, 16, 0x18000
	v_add_u32_e32 v0, s88, v237
	s_add_i32 s89, 16, 0x1c000
	ds_read_b128 v[132:135], v0
	ds_read_b128 v[136:139], v0 offset:1024
	ds_read_b128 v[152:155], v0 offset:2048
	ds_read_b128 v[156:159], v0 offset:3072
	v_add_u32_e32 v0, s89, v237
	ds_read_b128 v[160:163], v0
	ds_read_b128 v[164:167], v0 offset:1024
	ds_read_b128 v[168:171], v0 offset:2048
	ds_read_b128 v[172:175], v0 offset:3072
	s_add_u32 s30, s30, s18
	s_addc_u32 s31, s31, 0
	s_mov_b32 m0, s97
	v_lshl_add_u64 v[6:7], s[30:31], 0, v[142:143]
	ds_read_b128 v[176:179], v246 offset:32768
	ds_read_b128 v[180:183], v246 offset:33792
	ds_read_b128 v[184:187], v246 offset:34816
	ds_read_b128 v[188:191], v246 offset:35840
	ds_read_b128 v[192:195], v246 offset:36864
	ds_read_b128 v[196:199], v246 offset:37888
	ds_read_b128 v[200:203], v246 offset:38912
	ds_read_b128 v[204:207], v246 offset:39936
	global_load_lds_dwordx4 v[6:7], off
	v_lshl_add_u64 v[6:7], s[30:31], 0, v[144:145]
	s_mov_b32 m0, s58
	s_nop 0
	global_load_lds_dwordx4 v[6:7], off
	s_waitcnt vmcnt(8)
	s_waitcnt lgkmcnt(0)
	s_barrier
	s_setprio 1
	v_mfma_f32_16x16x32_bf16 v[128:131], v[132:135], v[176:179], v[128:131]
	v_mfma_f32_16x16x32_bf16 v[124:127], v[152:155], v[176:179], v[124:127]
	v_mfma_f32_16x16x32_bf16 v[112:115], v[132:135], v[184:187], v[112:115]
	v_mfma_f32_16x16x32_bf16 v[108:111], v[152:155], v[184:187], v[108:111]
	v_mfma_f32_16x16x32_bf16 v[96:99], v[132:135], v[192:195], v[96:99]
	v_mfma_f32_16x16x32_bf16 v[92:95], v[152:155], v[192:195], v[92:95]
	v_mfma_f32_16x16x32_bf16 v[80:83], v[132:135], v[200:203], v[80:83]
	v_mfma_f32_16x16x32_bf16 v[76:79], v[152:155], v[200:203], v[76:79]
	v_mfma_f32_16x16x32_bf16 v[128:131], v[136:139], v[180:183], v[128:131]
	v_mfma_f32_16x16x32_bf16 v[124:127], v[156:159], v[180:183], v[124:127]
	v_mfma_f32_16x16x32_bf16 v[112:115], v[136:139], v[188:191], v[112:115]
	v_mfma_f32_16x16x32_bf16 v[108:111], v[156:159], v[188:191], v[108:111]
	v_mfma_f32_16x16x32_bf16 v[96:99], v[136:139], v[196:199], v[96:99]
	v_mfma_f32_16x16x32_bf16 v[92:95], v[156:159], v[196:199], v[92:95]
	v_mfma_f32_16x16x32_bf16 v[80:83], v[136:139], v[204:207], v[80:83]
	v_mfma_f32_16x16x32_bf16 v[76:79], v[156:159], v[204:207], v[76:79]
	s_setprio 0
	s_setprio 1
	v_mfma_f32_16x16x32_bf16 v[120:123], v[160:163], v[176:179], v[120:123]
	v_mfma_f32_16x16x32_bf16 v[116:119], v[168:171], v[176:179], v[116:119]
	v_mfma_f32_16x16x32_bf16 v[104:107], v[160:163], v[184:187], v[104:107]
	v_mfma_f32_16x16x32_bf16 v[100:103], v[168:171], v[184:187], v[100:103]
	v_mfma_f32_16x16x32_bf16 v[88:91], v[160:163], v[192:195], v[88:91]
	v_mfma_f32_16x16x32_bf16 v[84:87], v[168:171], v[192:195], v[84:87]
	v_mfma_f32_16x16x32_bf16 v[72:75], v[160:163], v[200:203], v[72:75]
	v_mfma_f32_16x16x32_bf16 v[68:71], v[168:171], v[200:203], v[68:71]
	v_mfma_f32_16x16x32_bf16 v[120:123], v[164:167], v[180:183], v[120:123]
	v_mfma_f32_16x16x32_bf16 v[116:119], v[172:175], v[180:183], v[116:119]
	v_mfma_f32_16x16x32_bf16 v[104:107], v[164:167], v[188:191], v[104:107]
	v_mfma_f32_16x16x32_bf16 v[100:103], v[172:175], v[188:191], v[100:103]
	v_mfma_f32_16x16x32_bf16 v[88:91], v[164:167], v[196:199], v[88:91]
	v_mfma_f32_16x16x32_bf16 v[84:87], v[172:175], v[196:199], v[84:87]
	v_mfma_f32_16x16x32_bf16 v[72:75], v[164:167], v[204:207], v[72:75]
	v_mfma_f32_16x16x32_bf16 v[68:71], v[172:175], v[204:207], v[68:71]
	s_setprio 0
	s_barrier
	s_add_i32 s30, s88, s93
	v_lshl_add_u64 v[6:7], v[208:209], 0, s[36:37]
	s_mov_b32 m0, s30
	ds_read_b128 v[176:179], v246 offset:49152
	ds_read_b128 v[180:183], v246 offset:50176
	ds_read_b128 v[184:187], v246 offset:51200
	ds_read_b128 v[188:191], v246 offset:52224
	ds_read_b128 v[192:195], v246 offset:53248
	ds_read_b128 v[196:199], v246 offset:54272
	ds_read_b128 v[200:203], v246 offset:55296
	ds_read_b128 v[204:207], v246 offset:56320
	global_load_lds_dwordx4 v[6:7], off
	v_lshl_add_u64 v[6:7], v[210:211], 0, s[36:37]
	s_add_i32 m0, s30, 0x2000
	s_add_i32 s30, s89, s93
	global_load_lds_dwordx4 v[6:7], off
	v_lshl_add_u64 v[6:7], v[212:213], 0, s[36:37]
	s_mov_b32 m0, s30
	s_nop 0
	global_load_lds_dwordx4 v[6:7], off
	v_lshl_add_u64 v[6:7], v[214:215], 0, s[36:37]
	s_add_i32 m0, s30, 0x2000
	s_nop 0
	global_load_lds_dwordx4 v[6:7], off
	v_lshl_add_u64 v[6:7], v[224:225], 0, s[36:37]
	s_mov_b32 m0, s21
	s_nop 0
	global_load_lds_dwordx4 v[6:7], off
	v_lshl_add_u64 v[6:7], v[226:227], 0, s[36:37]
	s_mov_b32 m0, s33
	s_nop 0
	global_load_lds_dwordx4 v[6:7], off
	s_waitcnt vmcnt(8)
	s_waitcnt lgkmcnt(0)
	s_barrier
	s_setprio 1
	v_mfma_f32_16x16x32_bf16 v[64:67], v[132:135], v[176:179], v[64:67]
	v_mfma_f32_16x16x32_bf16 v[60:63], v[152:155], v[176:179], v[60:63]
	v_mfma_f32_16x16x32_bf16 v[48:51], v[132:135], v[184:187], v[48:51]
	v_mfma_f32_16x16x32_bf16 v[44:47], v[152:155], v[184:187], v[44:47]
	v_mfma_f32_16x16x32_bf16 v[32:35], v[132:135], v[192:195], v[32:35]
	v_mfma_f32_16x16x32_bf16 v[28:31], v[152:155], v[192:195], v[28:31]
	v_mfma_f32_16x16x32_bf16 v[16:19], v[132:135], v[200:203], v[16:19]
	v_mfma_f32_16x16x32_bf16 v[12:15], v[152:155], v[200:203], v[12:15]
	v_mfma_f32_16x16x32_bf16 v[64:67], v[136:139], v[180:183], v[64:67]
	v_mfma_f32_16x16x32_bf16 v[60:63], v[156:159], v[180:183], v[60:63]
	v_mfma_f32_16x16x32_bf16 v[48:51], v[136:139], v[188:191], v[48:51]
	v_mfma_f32_16x16x32_bf16 v[44:47], v[156:159], v[188:191], v[44:47]
	v_mfma_f32_16x16x32_bf16 v[32:35], v[136:139], v[196:199], v[32:35]
	v_mfma_f32_16x16x32_bf16 v[28:31], v[156:159], v[196:199], v[28:31]
	v_mfma_f32_16x16x32_bf16 v[16:19], v[136:139], v[204:207], v[16:19]
	v_mfma_f32_16x16x32_bf16 v[12:15], v[156:159], v[204:207], v[12:15]
	s_setprio 0
	s_setprio 1
	v_mfma_f32_16x16x32_bf16 v[56:59], v[160:163], v[176:179], v[56:59]
	v_mfma_f32_16x16x32_bf16 v[52:55], v[168:171], v[176:179], v[52:55]
	v_mfma_f32_16x16x32_bf16 v[40:43], v[160:163], v[184:187], v[40:43]
	v_mfma_f32_16x16x32_bf16 v[36:39], v[168:171], v[184:187], v[36:39]
	v_mfma_f32_16x16x32_bf16 v[24:27], v[160:163], v[192:195], v[24:27]
	v_mfma_f32_16x16x32_bf16 v[20:23], v[168:171], v[192:195], v[20:23]
	v_mfma_f32_16x16x32_bf16 v[6:9], v[160:163], v[200:203], v[8:11]
	v_mfma_f32_16x16x32_bf16 v[2:5], v[168:171], v[200:203], v[2:5]
	v_mfma_f32_16x16x32_bf16 v[56:59], v[164:167], v[180:183], v[56:59]
	v_mfma_f32_16x16x32_bf16 v[52:55], v[172:175], v[180:183], v[52:55]
	v_mfma_f32_16x16x32_bf16 v[40:43], v[164:167], v[188:191], v[40:43]
	v_mfma_f32_16x16x32_bf16 v[36:39], v[172:175], v[188:191], v[36:39]
	v_mfma_f32_16x16x32_bf16 v[24:27], v[164:167], v[196:199], v[24:27]
	v_mfma_f32_16x16x32_bf16 v[20:23], v[172:175], v[196:199], v[20:23]
	v_mfma_f32_16x16x32_bf16 v[8:11], v[164:167], v[204:207], v[6:9]
	v_mfma_f32_16x16x32_bf16 v[4:7], v[172:175], v[204:207], v[2:5]
	s_setprio 0
	s_barrier
	s_andn2_b64 vcc, exec, s[22:23]
	s_cbranch_vccnz .LBB0_1202
